# mod_job k-loop: next 16 weight rows prefetched (register double buffer)
# speedup vs baseline: 1.0080x; 1.0027x over previous
; __device__ void mod_job(const Params& p, int job, char* smem) {
;     ...
;   for (int k = kq * 128; k < kq * 128 + 128; k += 16) {
;     float wv[16];
; #pragma unroll
;     for (int u = 0; u < 16; ++u) wv[u] = w[(size_t)(k + u) * 6144];
; #pragma unroll
;     for (int u = 0; u < 16; ++u)
; #pragma unroll
;       for (int r = 0; r < 17; ++r) acc[r] += sc[r * 1024 + k + u] * wv[u];
;   }
.LBB0_47:
	s_or_b64 exec, exec, s[2:3]
	s_mul_hi_i32 s2, s39, 0x2aaaaaab
	s_lshr_b32 s3, s2, 31
	s_ashr_i32 s8, s2, 4
	s_add_i32 s8, s8, s3
	s_mul_i32 s2, s8, 0x60
	s_sub_i32 s9, s39, s2
	s_lshl_b32 s4, s9, 6
	s_ashr_i32 s5, s4, 31
	s_mul_i32 s7, s8, 0x1800000
	s_lshl_b64 s[2:3], s[4:5], 2
	s_mul_hi_i32 s6, s8, 0x1800000
	s_add_u32 s2, s2, s7
	v_ashrrev_i32_e32 v83, 6, v82
	s_addc_u32 s3, s3, s6
	v_lshlrev_b32_e32 v4, 7, v83
	v_mov_b64_e32 v[2:3], s[2:3]
	s_movk_i32 s2, 0x6000
	v_and_b32_e32 v79, 63, v82
	v_mad_i64_i32 v[2:3], s[2:3], v4, s2, v[2:3]
	v_lshl_or_b32 v2, v79, 2, v2
	v_mov_b32_e32 v129, 0
	v_or_b32_e32 v126, 0x70, v4
	v_add_u32_e32 v127, -16, v4
	v_lshl_add_u32 v128, v83, 9, 0
	v_lshl_add_u64 v[84:85], s[30:31], 0, v[2:3]
	s_mov_b64 s[6:7], 0
	v_mov_b32_e32 v2, 0
	v_mov_b32_e32 v3, v129
	v_mov_b32_e32 v10, 0
	v_mov_b32_e32 v11, v129
	v_mov_b32_e32 v18, 0
	v_mov_b32_e32 v19, v129
	v_mov_b32_e32 v26, 0
	v_mov_b32_e32 v27, v129
	v_mov_b32_e32 v96, 0
	v_mov_b32_e32 v97, v129
	v_mov_b32_e32 v98, 0
	v_mov_b32_e32 v99, v129
	v_mov_b32_e32 v100, 0
	v_mov_b32_e32 v101, v129
	v_mov_b32_e32 v102, 0
	v_mov_b32_e32 v103, v129
	s_waitcnt lgkmcnt(0)
	s_barrier
	s_mov_b32 s101, 0
.LBB0_48:
	s_cmp_lg_u32 s101, 0
	s_cbranch_scc1 .Lmodk_copy
	s_mov_b32 s2, 0xfffa6000
	v_add_co_u32_e32 v4, vcc, s2, v84
	s_mov_b32 s2, 0xfffac000
	s_nop 0
	v_addc_co_u32_e32 v5, vcc, -1, v85, vcc
	global_load_dword v110, v[4:5], off
	v_add_co_u32_e32 v4, vcc, s2, v84
	s_mov_b32 s2, 0xfffb2000
	s_nop 0
	v_addc_co_u32_e32 v5, vcc, -1, v85, vcc
	global_load_dword v112, v[4:5], off
	v_add_co_u32_e32 v4, vcc, s2, v84
	s_mov_b32 s2, 0xfffb8000
	s_nop 0
	v_addc_co_u32_e32 v5, vcc, -1, v85, vcc
	global_load_dword v114, v[4:5], off
	v_add_co_u32_e32 v4, vcc, s2, v84
	s_mov_b32 s2, 0xfffbe000
	s_nop 0
	v_addc_co_u32_e32 v5, vcc, -1, v85, vcc
	global_load_dword v108, v[4:5], off
	v_add_co_u32_e32 v4, vcc, s2, v84
	s_mov_b32 s2, 0xfffc4000
	s_nop 0
	v_addc_co_u32_e32 v5, vcc, -1, v85, vcc
	global_load_dword v116, v[4:5], off
	v_add_co_u32_e32 v4, vcc, s2, v84
	s_mov_b32 s2, 0xfffca000
	s_nop 0
	v_addc_co_u32_e32 v5, vcc, -1, v85, vcc
	global_load_dword v94, v[4:5], off
	v_add_co_u32_e32 v4, vcc, s2, v84
	s_mov_b32 s2, 0xfffd0000
	s_nop 0
	v_addc_co_u32_e32 v5, vcc, -1, v85, vcc
	global_load_dword v95, v[4:5], off
	v_add_co_u32_e32 v4, vcc, s2, v84
	s_mov_b32 s2, 0xfffd6000
	s_nop 0
	v_addc_co_u32_e32 v5, vcc, -1, v85, vcc
	global_load_dword v92, v[4:5], off
	v_add_co_u32_e32 v4, vcc, s2, v84
	s_mov_b32 s2, 0xfffdc000
	s_nop 0
	v_addc_co_u32_e32 v5, vcc, -1, v85, vcc
	global_load_dword v93, v[4:5], off
	v_add_co_u32_e32 v4, vcc, s2, v84
	s_mov_b32 s2, 0xfffe2000
	s_nop 0
	v_addc_co_u32_e32 v5, vcc, -1, v85, vcc
	global_load_dword v88, v[4:5], off
	v_add_co_u32_e32 v4, vcc, s2, v84
	s_mov_b32 s2, 0xfffe8000
	s_nop 0
	v_addc_co_u32_e32 v5, vcc, -1, v85, vcc
	global_load_dword v89, v[4:5], off
	v_add_co_u32_e32 v4, vcc, s2, v84
	s_mov_b32 s2, 0xfffee000
	s_nop 0
	v_addc_co_u32_e32 v5, vcc, -1, v85, vcc
	global_load_dword v90, v[4:5], off
	v_add_co_u32_e32 v4, vcc, s2, v84
	s_mov_b32 s2, 0xffff4000
	s_nop 0
	v_addc_co_u32_e32 v5, vcc, -1, v85, vcc
	global_load_dword v91, v[4:5], off
	v_add_co_u32_e32 v4, vcc, s2, v84
	s_movk_i32 s2, 0xa000
	s_nop 0
	v_addc_co_u32_e32 v5, vcc, -1, v85, vcc
	global_load_dword v86, v[4:5], off
	v_add_co_u32_e32 v4, vcc, s2, v84
	v_add_u32_e32 v109, 0x1000c, v128
	s_nop 0
	v_addc_co_u32_e32 v5, vcc, -1, v85, vcc
	global_load_dword v87, v[4:5], off
	global_load_dword v74, v[84:85], off
	s_branch .Lmodk_cont
.Lmodk_copy:
	v_add_u32_e32 v109, 0x1000c, v128
	s_waitcnt vmcnt(0)
	v_mov_b32_e32 v110, v140
	v_mov_b32_e32 v112, v141
	v_mov_b32_e32 v114, v142
	v_mov_b32_e32 v108, v143
	v_mov_b32_e32 v116, v144
	v_mov_b32_e32 v94, v145
	v_mov_b32_e32 v95, v146
	v_mov_b32_e32 v92, v147
	v_mov_b32_e32 v93, v148
	v_mov_b32_e32 v88, v149
	v_mov_b32_e32 v89, v150
	v_mov_b32_e32 v90, v151
	v_mov_b32_e32 v91, v152
	v_mov_b32_e32 v86, v153
	v_mov_b32_e32 v87, v154
	v_mov_b32_e32 v74, v155
.Lmodk_cont:
	v_add_u32_e32 v158, 16, v127
	v_mov_b32_e32 v159, 0x60000
	v_cmp_lt_i32_e64 s[98:99], v158, v126
	s_mov_b32 s101, 1
	s_nop 1
	v_cndmask_b32_e64 v158, 0, v159, s[98:99]
	v_mov_b32_e32 v159, 0
	v_lshl_add_u64 v[156:157], v[84:85], 0, v[158:159]
	s_mov_b32 s2, 0xfffa6000
	v_add_co_u32_e32 v158, vcc, s2, v156
	s_mov_b32 s2, 0xfffac000
	s_nop 0
	v_addc_co_u32_e32 v159, vcc, -1, v157, vcc
	global_load_dword v140, v[158:159], off
	v_add_co_u32_e32 v158, vcc, s2, v156
	s_mov_b32 s2, 0xfffb2000
	s_nop 0
	v_addc_co_u32_e32 v159, vcc, -1, v157, vcc
	global_load_dword v141, v[158:159], off
	v_add_co_u32_e32 v158, vcc, s2, v156
	s_mov_b32 s2, 0xfffb8000
	s_nop 0
	v_addc_co_u32_e32 v159, vcc, -1, v157, vcc
	global_load_dword v142, v[158:159], off
	v_add_co_u32_e32 v158, vcc, s2, v156
	s_mov_b32 s2, 0xfffbe000
	s_nop 0
	v_addc_co_u32_e32 v159, vcc, -1, v157, vcc
	global_load_dword v143, v[158:159], off
	v_add_co_u32_e32 v158, vcc, s2, v156
	s_mov_b32 s2, 0xfffc4000
	s_nop 0
	v_addc_co_u32_e32 v159, vcc, -1, v157, vcc
	global_load_dword v144, v[158:159], off
	v_add_co_u32_e32 v158, vcc, s2, v156
	s_mov_b32 s2, 0xfffca000
	s_nop 0
	v_addc_co_u32_e32 v159, vcc, -1, v157, vcc
	global_load_dword v145, v[158:159], off
	v_add_co_u32_e32 v158, vcc, s2, v156
	s_mov_b32 s2, 0xfffd0000
	s_nop 0
	v_addc_co_u32_e32 v159, vcc, -1, v157, vcc
	global_load_dword v146, v[158:159], off
	v_add_co_u32_e32 v158, vcc, s2, v156
	s_mov_b32 s2, 0xfffd6000
	s_nop 0
	v_addc_co_u32_e32 v159, vcc, -1, v157, vcc
	global_load_dword v147, v[158:159], off
	v_add_co_u32_e32 v158, vcc, s2, v156
	s_mov_b32 s2, 0xfffdc000
	s_nop 0
	v_addc_co_u32_e32 v159, vcc, -1, v157, vcc
	global_load_dword v148, v[158:159], off
	v_add_co_u32_e32 v158, vcc, s2, v156
	s_mov_b32 s2, 0xfffe2000
	s_nop 0
	v_addc_co_u32_e32 v159, vcc, -1, v157, vcc
	global_load_dword v149, v[158:159], off
	v_add_co_u32_e32 v158, vcc, s2, v156
	s_mov_b32 s2, 0xfffe8000
	s_nop 0
	v_addc_co_u32_e32 v159, vcc, -1, v157, vcc
	global_load_dword v150, v[158:159], off
	v_add_co_u32_e32 v158, vcc, s2, v156
	s_mov_b32 s2, 0xfffee000
	s_nop 0
	v_addc_co_u32_e32 v159, vcc, -1, v157, vcc
	global_load_dword v151, v[158:159], off
	v_add_co_u32_e32 v158, vcc, s2, v156
	s_mov_b32 s2, 0xffff4000
	s_nop 0
	v_addc_co_u32_e32 v159, vcc, -1, v157, vcc
	global_load_dword v152, v[158:159], off
	v_add_co_u32_e32 v158, vcc, s2, v156
	s_movk_i32 s2, 0xa000
	s_nop 0
	v_addc_co_u32_e32 v159, vcc, -1, v157, vcc
	global_load_dword v153, v[158:159], off
	v_add_co_u32_e32 v158, vcc, s2, v156
	s_nop 0
	v_addc_co_u32_e32 v159, vcc, -1, v157, vcc
	global_load_dword v154, v[158:159], off
	global_load_dword v155, v[156:157], off
	v_add_u32_e32 v4, 0x10000, v128
	ds_read_b96 v[4:6], v4
	v_add_u32_e32 v127, 16, v127
	s_mov_b64 s[2:3], 0x60000
	v_cmp_ge_i32_e32 vcc, v127, v126
	v_lshl_add_u64 v[84:85], v[84:85], 0, s[2:3]
	s_waitcnt vmcnt(31) lgkmcnt(0)
; __device__ void mod_job(const Params& p, int job, char* smem) {
;     ...
;     for (int u = 0; u < 16; ++u)
; #pragma unroll
;       for (int r = 0; r < 17; ++r) acc[r] += sc[r * 1024 + k + u] * wv[u];
	v_fmac_f32_e32 v129, v110, v4
	s_waitcnt vmcnt(30)
	v_fmac_f32_e32 v129, v112, v5
	s_waitcnt vmcnt(29)
	v_fmac_f32_e32 v129, v114, v6
	ds_read_b128 v[4:7], v128
	ds_read_b128 v[66:69], v128 offset:16
	ds_read_b128 v[62:65], v128 offset:32
	ds_read_b128 v[50:53], v128 offset:48
	ds_read_b128 v[70:73], v128 offset:4112
	ds_read_b128 v[12:15], v128 offset:4096
	s_waitcnt lgkmcnt(5)
	v_mov_b32_e32 v8, v4
	v_mov_b32_e32 v4, v6
	s_or_b64 s[6:7], vcc, s[6:7]
	s_waitcnt lgkmcnt(0)
	v_mov_b32_e32 v9, v12
	v_pk_fma_f32 v[2:3], v[110:111], v[8:9], v[2:3] op_sel_hi:[0,1,1]
	v_mov_b32_e32 v12, v5
	v_pk_fma_f32 v[2:3], v[112:113], v[12:13], v[2:3] op_sel_hi:[0,1,1]
	v_mov_b32_e32 v5, v14
	v_pk_fma_f32 v[2:3], v[114:115], v[4:5], v[2:3] op_sel_hi:[0,1,1]
	v_mov_b32_e32 v14, v7
	s_waitcnt vmcnt(28)
	v_pk_fma_f32 v[2:3], v[108:109], v[14:15], v[2:3] op_sel_hi:[0,1,1]
	v_mov_b32_e32 v4, v66
	v_mov_b32_e32 v5, v70
	s_waitcnt vmcnt(27)
	v_pk_fma_f32 v[120:121], v[116:117], v[4:5], v[2:3] op_sel_hi:[0,1,1]
	ds_read_b128 v[54:57], v128 offset:8208
	ds_read_b128 v[58:61], v128 offset:12304
	ds_read_b128 v[2:5], v128 offset:8192
	ds_read_b128 v[6:9], v128 offset:12288
	v_mov_b32_e32 v70, v67
	s_waitcnt lgkmcnt(1)
	v_mov_b32_e32 v12, v2
	s_waitcnt lgkmcnt(0)
	v_mov_b32_e32 v13, v6
	v_pk_fma_f32 v[10:11], v[110:111], v[12:13], v[10:11] op_sel_hi:[0,1,1]
	v_mov_b32_e32 v6, v3
	v_pk_fma_f32 v[2:3], v[112:113], v[6:7], v[10:11] op_sel_hi:[0,1,1]
	v_mov_b32_e32 v6, v4
	v_mov_b32_e32 v7, v8
	v_pk_fma_f32 v[2:3], v[114:115], v[6:7], v[2:3] op_sel_hi:[0,1,1]
	v_mov_b32_e32 v8, v5
	v_pk_fma_f32 v[2:3], v[108:109], v[8:9], v[2:3] op_sel_hi:[0,1,1]
	v_mov_b32_e32 v4, v54
	v_mov_b32_e32 v5, v58
	v_pk_fma_f32 v[118:119], v[116:117], v[4:5], v[2:3] op_sel_hi:[0,1,1]
	ds_read_b128 v[42:45], v128 offset:16400
	ds_read_b128 v[46:49], v128 offset:20496
	ds_read_b128 v[2:5], v128 offset:16384
	ds_read_b128 v[6:9], v128 offset:20480
	s_waitcnt vmcnt(23)
	v_mov_b32_e32 v66, v93
	v_mov_b32_e32 v58, v55
	s_waitcnt lgkmcnt(1)
	v_mov_b32_e32 v10, v2
	s_waitcnt lgkmcnt(0)
	v_mov_b32_e32 v11, v6
	v_pk_fma_f32 v[10:11], v[110:111], v[10:11], v[18:19] op_sel_hi:[0,1,1]
	v_mov_b32_e32 v6, v3
	v_pk_fma_f32 v[2:3], v[112:113], v[6:7], v[10:11] op_sel_hi:[0,1,1]
	v_mov_b32_e32 v6, v4
	v_mov_b32_e32 v7, v8
	v_pk_fma_f32 v[2:3], v[114:115], v[6:7], v[2:3] op_sel_hi:[0,1,1]
	v_mov_b32_e32 v8, v5
	v_pk_fma_f32 v[2:3], v[108:109], v[8:9], v[2:3] op_sel_hi:[0,1,1]
	v_mov_b32_e32 v4, v42
	v_mov_b32_e32 v5, v46
	v_pk_fma_f32 v[106:107], v[116:117], v[4:5], v[2:3] op_sel_hi:[0,1,1]
	ds_read_b128 v[34:37], v128 offset:24592
	ds_read_b128 v[38:41], v128 offset:28688
	ds_read_b128 v[2:5], v128 offset:24576
	ds_read_b128 v[6:9], v128 offset:28672
	v_mov_b32_e32 v46, v43
	s_waitcnt lgkmcnt(1)
	v_mov_b32_e32 v10, v2
	s_waitcnt lgkmcnt(0)
	v_mov_b32_e32 v11, v6
	v_pk_fma_f32 v[10:11], v[110:111], v[10:11], v[26:27] op_sel_hi:[0,1,1]
	v_mov_b32_e32 v6, v3
	v_pk_fma_f32 v[2:3], v[112:113], v[6:7], v[10:11] op_sel_hi:[0,1,1]
	v_mov_b32_e32 v6, v4
	v_mov_b32_e32 v7, v8
	v_pk_fma_f32 v[2:3], v[114:115], v[6:7], v[2:3] op_sel_hi:[0,1,1]
	v_mov_b32_e32 v8, v5
	v_pk_fma_f32 v[2:3], v[108:109], v[8:9], v[2:3] op_sel_hi:[0,1,1]
	v_mov_b32_e32 v4, v34
	v_mov_b32_e32 v5, v38
	v_pk_fma_f32 v[104:105], v[116:117], v[4:5], v[2:3] op_sel_hi:[0,1,1]
	ds_read_b128 v[26:29], v128 offset:32784
	ds_read_b128 v[30:33], v128 offset:36880
	ds_read_b128 v[2:5], v128 offset:32768
	ds_read_b128 v[6:9], v128 offset:36864
	v_mov_b32_e32 v34, v95
	s_waitcnt vmcnt(19)
	v_mov_b32_e32 v54, v91
	s_waitcnt vmcnt(17)
	v_mov_b32_e32 v42, v87
	s_waitcnt lgkmcnt(1)
	v_mov_b32_e32 v10, v2
	s_waitcnt lgkmcnt(0)
	v_mov_b32_e32 v11, v6
	v_pk_fma_f32 v[10:11], v[110:111], v[10:11], v[96:97] op_sel_hi:[0,1,1]
	v_mov_b32_e32 v6, v3
	v_pk_fma_f32 v[2:3], v[112:113], v[6:7], v[10:11] op_sel_hi:[0,1,1]
	v_mov_b32_e32 v6, v4
	v_mov_b32_e32 v7, v8
	v_pk_fma_f32 v[2:3], v[114:115], v[6:7], v[2:3] op_sel_hi:[0,1,1]
	v_mov_b32_e32 v8, v5
	v_pk_fma_f32 v[2:3], v[108:109], v[8:9], v[2:3] op_sel_hi:[0,1,1]
	v_mov_b32_e32 v4, v26
	v_mov_b32_e32 v5, v30
	v_pk_fma_f32 v[96:97], v[116:117], v[4:5], v[2:3] op_sel_hi:[0,1,1]
	ds_read_b128 v[18:21], v128 offset:40976
	ds_read_b128 v[22:25], v128 offset:45072
	ds_read_b128 v[2:5], v128 offset:40960
	ds_read_b128 v[6:9], v128 offset:45056
	v_mov_b32_e32 v30, v27
	v_mov_b32_e32 v26, v44
	v_mov_b32_e32 v27, v48
	s_waitcnt lgkmcnt(1)
	v_mov_b32_e32 v10, v2
	s_waitcnt lgkmcnt(0)
	v_mov_b32_e32 v11, v6
	v_pk_fma_f32 v[10:11], v[110:111], v[10:11], v[98:99] op_sel_hi:[0,1,1]
	v_mov_b32_e32 v6, v3
	v_pk_fma_f32 v[2:3], v[112:113], v[6:7], v[10:11] op_sel_hi:[0,1,1]
	v_mov_b32_e32 v6, v4
	v_mov_b32_e32 v7, v8
	v_pk_fma_f32 v[2:3], v[114:115], v[6:7], v[2:3] op_sel_hi:[0,1,1]
	v_mov_b32_e32 v8, v5
	v_pk_fma_f32 v[2:3], v[108:109], v[8:9], v[2:3] op_sel_hi:[0,1,1]
	v_mov_b32_e32 v4, v18
	v_mov_b32_e32 v5, v22
	v_pk_fma_f32 v[98:99], v[116:117], v[4:5], v[2:3] op_sel_hi:[0,1,1]
	ds_read_b128 v[10:13], v128 offset:49168
	ds_read_b128 v[14:17], v128 offset:53264
	ds_read_b128 v[2:5], v128 offset:49152
	ds_read_b128 v[6:9], v128 offset:53248
	v_mov_b32_e32 v22, v19
	v_mov_b32_e32 v18, v56
	v_mov_b32_e32 v19, v60
	s_waitcnt lgkmcnt(1)
	v_mov_b32_e32 v130, v2
	s_waitcnt lgkmcnt(0)
; __device__ void mod_job(const Params& p, int job, char* smem) {
;     ...
;     for (int u = 0; u < 16; ++u)
; #pragma unroll
;       for (int r = 0; r < 17; ++r) acc[r] += sc[r * 1024 + k + u] * wv[u];
	v_mov_b32_e32 v131, v6
	v_pk_fma_f32 v[100:101], v[110:111], v[130:131], v[100:101] op_sel_hi:[0,1,1]
	v_mov_b32_e32 v6, v3
	v_pk_fma_f32 v[2:3], v[112:113], v[6:7], v[100:101] op_sel_hi:[0,1,1]
	v_mov_b32_e32 v6, v4
	v_mov_b32_e32 v7, v8
	v_pk_fma_f32 v[2:3], v[114:115], v[6:7], v[2:3] op_sel_hi:[0,1,1]
	v_mov_b32_e32 v8, v5
	v_pk_fma_f32 v[2:3], v[108:109], v[8:9], v[2:3] op_sel_hi:[0,1,1]
	v_mov_b32_e32 v4, v10
	v_mov_b32_e32 v5, v14
	v_pk_fma_f32 v[100:101], v[116:117], v[4:5], v[2:3] op_sel_hi:[0,1,1]
	ds_read_b128 v[2:5], v128 offset:57360
	ds_read_b128 v[6:9], v128 offset:61456
	ds_read_b128 v[130:133], v128 offset:57344
	ds_read_b128 v[134:137], v128 offset:61440
	v_mov_b32_e32 v14, v11
	v_mov_b32_e32 v11, v72
	v_mov_b32_e32 v72, v69
	s_waitcnt lgkmcnt(1)
	v_mov_b32_e32 v138, v130
	s_waitcnt lgkmcnt(0)
	v_mov_b32_e32 v139, v134
	v_pk_fma_f32 v[102:103], v[110:111], v[138:139], v[102:103] op_sel_hi:[0,1,1]
	v_mov_b32_e32 v134, v131
	v_pk_fma_f32 v[102:103], v[112:113], v[134:135], v[102:103] op_sel_hi:[0,1,1]
	v_mov_b32_e32 v130, v132
	v_mov_b32_e32 v131, v136
	v_pk_fma_f32 v[102:103], v[114:115], v[130:131], v[102:103] op_sel_hi:[0,1,1]
	v_mov_b32_e32 v136, v133
	v_pk_fma_f32 v[102:103], v[108:109], v[136:137], v[102:103] op_sel_hi:[0,1,1]
	v_mov_b32_e32 v130, v2
	v_mov_b32_e32 v131, v6
	v_pk_fma_f32 v[102:103], v[116:117], v[130:131], v[102:103] op_sel_hi:[0,1,1]
	ds_read2_b32 v[130:131], v109 offset1:1
	v_mov_b32_e32 v109, v116
	v_mov_b32_e32 v6, v3
	v_mov_b32_e32 v60, v57
	v_mov_b32_e32 v48, v45
	s_waitcnt lgkmcnt(0)
	v_pk_mul_f32 v[108:109], v[108:109], v[130:131]
	v_mov_b32_e32 v38, v35
	v_add_f32_e32 v2, v129, v108
	v_add_f32_e32 v10, v2, v109
	v_add_u32_e32 v2, 0x10014, v128
	ds_read2_b32 v[2:3], v2 offset1:1
	v_pk_fma_f32 v[30:31], v[94:95], v[30:31], v[96:97] op_sel_hi:[0,1,1]
	v_pk_fma_f32 v[22:23], v[94:95], v[22:23], v[98:99] op_sel_hi:[0,1,1]
	v_pk_fma_f32 v[14:15], v[94:95], v[14:15], v[100:101] op_sel_hi:[0,1,1]
	v_pk_fma_f32 v[6:7], v[94:95], v[6:7], v[102:103] op_sel_hi:[0,1,1]
	s_waitcnt lgkmcnt(0)
	v_pk_mul_f32 v[2:3], v[94:95], v[2:3]
	s_nop 0
	v_add_f32_e32 v2, v10, v2
	v_add_f32_e32 v10, v2, v3
	v_add_u32_e32 v2, 0x1001c, v128
	ds_read2_b32 v[2:3], v2 offset1:1
	s_waitcnt lgkmcnt(0)
	v_pk_mul_f32 v[2:3], v[92:93], v[2:3]
	s_nop 0
	v_add_f32_e32 v2, v10, v2
	v_add_f32_e32 v10, v2, v3
	v_add_u32_e32 v2, 0x10024, v128
	ds_read2_b32 v[2:3], v2 offset1:1
	s_waitcnt lgkmcnt(0)
	v_pk_mul_f32 v[2:3], v[88:89], v[2:3]
	s_nop 0
	v_add_f32_e32 v2, v10, v2
	v_add_f32_e32 v10, v2, v3
	v_add_u32_e32 v2, 0x1002c, v128
	ds_read2_b32 v[2:3], v2 offset1:1
	s_waitcnt lgkmcnt(0)
	v_pk_mul_f32 v[2:3], v[90:91], v[2:3]
	s_nop 0
	v_add_f32_e32 v2, v10, v2
	v_add_f32_e32 v10, v2, v3
	v_add_u32_e32 v2, 0x10034, v128
	ds_read2_b32 v[2:3], v2 offset1:1
	s_waitcnt lgkmcnt(0)
	v_pk_mul_f32 v[2:3], v[86:87], v[2:3]
	s_nop 0
	v_add_f32_e32 v2, v10, v2
	v_add_f32_e32 v129, v2, v3
	v_pk_fma_f32 v[2:3], v[94:95], v[70:71], v[120:121] op_sel_hi:[0,1,1]
	v_mov_b32_e32 v10, v68
	ds_read_b128 v[68:71], v128 offset:4128
	v_pk_fma_f32 v[2:3], v[34:35], v[10:11], v[2:3] op_sel_hi:[0,1,1]
	v_pk_fma_f32 v[2:3], v[92:93], v[72:73], v[2:3] op_sel_hi:[0,1,1]
	v_mov_b32_e32 v10, v62
	v_mov_b32_e32 v62, v89
	s_waitcnt lgkmcnt(0)
	v_mov_b32_e32 v11, v68
	v_pk_fma_f32 v[2:3], v[66:67], v[10:11], v[2:3] op_sel_hi:[0,1,1]
	v_mov_b32_e32 v68, v63
	v_pk_fma_f32 v[2:3], v[88:89], v[68:69], v[2:3] op_sel_hi:[0,1,1]
	v_mov_b32_e32 v10, v64
	v_mov_b32_e32 v11, v70
	v_pk_fma_f32 v[2:3], v[62:63], v[10:11], v[2:3] op_sel_hi:[0,1,1]
	v_mov_b32_e32 v70, v65
	v_pk_fma_f32 v[2:3], v[90:91], v[70:71], v[2:3] op_sel_hi:[0,1,1]
	ds_read_b128 v[68:71], v128 offset:4144
	v_mov_b32_e32 v10, v50
	s_waitcnt lgkmcnt(0)
	v_mov_b32_e32 v11, v68
	v_pk_fma_f32 v[2:3], v[54:55], v[10:11], v[2:3] op_sel_hi:[0,1,1]
	v_mov_b32_e32 v68, v51
	v_pk_fma_f32 v[2:3], v[86:87], v[68:69], v[2:3] op_sel_hi:[0,1,1]
	v_mov_b32_e32 v10, v52
	v_mov_b32_e32 v11, v70
	v_pk_fma_f32 v[2:3], v[42:43], v[10:11], v[2:3] op_sel_hi:[0,1,1]
	v_mov_b32_e32 v70, v53
	v_pk_fma_f32 v[10:11], v[94:95], v[58:59], v[118:119] op_sel_hi:[0,1,1]
	ds_read_b128 v[50:53], v128 offset:8224
	ds_read_b128 v[56:59], v128 offset:12320
	v_pk_fma_f32 v[10:11], v[34:35], v[18:19], v[10:11] op_sel_hi:[0,1,1]
	v_pk_fma_f32 v[10:11], v[92:93], v[60:61], v[10:11] op_sel_hi:[0,1,1]
	s_waitcnt vmcnt(16)
	v_pk_fma_f32 v[2:3], v[74:75], v[70:71], v[2:3] op_sel_hi:[0,1,1]
	s_waitcnt lgkmcnt(1)
	v_mov_b32_e32 v18, v50
	s_waitcnt lgkmcnt(0)
	v_mov_b32_e32 v19, v56
	v_pk_fma_f32 v[10:11], v[66:67], v[18:19], v[10:11] op_sel_hi:[0,1,1]
	v_mov_b32_e32 v56, v51
	v_pk_fma_f32 v[10:11], v[88:89], v[56:57], v[10:11] op_sel_hi:[0,1,1]
	v_mov_b32_e32 v18, v52
	v_mov_b32_e32 v19, v58
	v_pk_fma_f32 v[10:11], v[62:63], v[18:19], v[10:11] op_sel_hi:[0,1,1]
	v_mov_b32_e32 v58, v53
	v_pk_fma_f32 v[10:11], v[90:91], v[58:59], v[10:11] op_sel_hi:[0,1,1]
	ds_read_b128 v[50:53], v128 offset:8240
	ds_read_b128 v[56:59], v128 offset:12336
	s_waitcnt lgkmcnt(1)
	v_mov_b32_e32 v18, v50
	s_waitcnt lgkmcnt(0)
	v_mov_b32_e32 v19, v56
	v_pk_fma_f32 v[10:11], v[54:55], v[18:19], v[10:11] op_sel_hi:[0,1,1]
	v_mov_b32_e32 v56, v51
	v_pk_fma_f32 v[10:11], v[86:87], v[56:57], v[10:11] op_sel_hi:[0,1,1]
	v_mov_b32_e32 v18, v52
	v_mov_b32_e32 v19, v58
	v_pk_fma_f32 v[10:11], v[42:43], v[18:19], v[10:11] op_sel_hi:[0,1,1]
	v_pk_fma_f32 v[18:19], v[94:95], v[46:47], v[106:107] op_sel_hi:[0,1,1]
	v_pk_fma_f32 v[18:19], v[34:35], v[26:27], v[18:19] op_sel_hi:[0,1,1]
	v_pk_fma_f32 v[18:19], v[92:93], v[48:49], v[18:19] op_sel_hi:[0,1,1]
	ds_read_b128 v[44:47], v128 offset:16416
	ds_read_b128 v[48:51], v128 offset:20512
	v_mov_b32_e32 v58, v53
	v_pk_fma_f32 v[10:11], v[74:75], v[58:59], v[10:11] op_sel_hi:[0,1,1]
	s_waitcnt lgkmcnt(1)
; __device__ void mod_job(const Params& p, int job, char* smem) {
;     ...
;     for (int u = 0; u < 16; ++u)
; #pragma unroll
;       for (int r = 0; r < 17; ++r) acc[r] += sc[r * 1024 + k + u] * wv[u];
	v_mov_b32_e32 v26, v44
	s_waitcnt lgkmcnt(0)
	v_mov_b32_e32 v27, v48
	v_pk_fma_f32 v[18:19], v[66:67], v[26:27], v[18:19] op_sel_hi:[0,1,1]
	v_mov_b32_e32 v48, v45
	v_pk_fma_f32 v[18:19], v[88:89], v[48:49], v[18:19] op_sel_hi:[0,1,1]
	v_mov_b32_e32 v26, v46
	v_mov_b32_e32 v27, v50
	v_pk_fma_f32 v[18:19], v[62:63], v[26:27], v[18:19] op_sel_hi:[0,1,1]
	v_mov_b32_e32 v50, v47
	v_pk_fma_f32 v[18:19], v[90:91], v[50:51], v[18:19] op_sel_hi:[0,1,1]
	ds_read_b128 v[44:47], v128 offset:16432
	ds_read_b128 v[48:51], v128 offset:20528
	s_waitcnt lgkmcnt(1)
	v_mov_b32_e32 v26, v44
	s_waitcnt lgkmcnt(0)
	v_mov_b32_e32 v27, v48
	v_pk_fma_f32 v[18:19], v[54:55], v[26:27], v[18:19] op_sel_hi:[0,1,1]
	v_mov_b32_e32 v48, v45
	v_pk_fma_f32 v[18:19], v[86:87], v[48:49], v[18:19] op_sel_hi:[0,1,1]
	v_mov_b32_e32 v26, v46
	v_mov_b32_e32 v27, v50
	v_pk_fma_f32 v[18:19], v[42:43], v[26:27], v[18:19] op_sel_hi:[0,1,1]
	v_pk_fma_f32 v[26:27], v[94:95], v[38:39], v[104:105] op_sel_hi:[0,1,1]
	v_mov_b32_e32 v38, v36
	v_mov_b32_e32 v39, v40
	v_mov_b32_e32 v50, v47
	v_pk_fma_f32 v[26:27], v[34:35], v[38:39], v[26:27] op_sel_hi:[0,1,1]
	v_mov_b32_e32 v40, v37
	ds_read_b128 v[36:39], v128 offset:24608
	ds_read_b128 v[44:47], v128 offset:28704
	v_pk_fma_f32 v[26:27], v[92:93], v[40:41], v[26:27] op_sel_hi:[0,1,1]
	v_pk_fma_f32 v[18:19], v[74:75], v[50:51], v[18:19] op_sel_hi:[0,1,1]
	s_waitcnt lgkmcnt(1)
	v_mov_b32_e32 v40, v36
	s_waitcnt lgkmcnt(0)
	v_mov_b32_e32 v41, v44
	v_pk_fma_f32 v[26:27], v[66:67], v[40:41], v[26:27] op_sel_hi:[0,1,1]
	v_mov_b32_e32 v44, v37
	v_pk_fma_f32 v[26:27], v[88:89], v[44:45], v[26:27] op_sel_hi:[0,1,1]
	v_mov_b32_e32 v36, v38
	v_mov_b32_e32 v37, v46
	v_pk_fma_f32 v[26:27], v[62:63], v[36:37], v[26:27] op_sel_hi:[0,1,1]
	v_mov_b32_e32 v46, v39
	v_pk_fma_f32 v[26:27], v[90:91], v[46:47], v[26:27] op_sel_hi:[0,1,1]
	ds_read_b128 v[36:39], v128 offset:24624
	ds_read_b128 v[44:47], v128 offset:28720
	s_waitcnt lgkmcnt(1)
	v_mov_b32_e32 v40, v36
	s_waitcnt lgkmcnt(0)
	v_mov_b32_e32 v41, v44
	v_pk_fma_f32 v[26:27], v[54:55], v[40:41], v[26:27] op_sel_hi:[0,1,1]
	v_mov_b32_e32 v44, v37
	v_pk_fma_f32 v[26:27], v[86:87], v[44:45], v[26:27] op_sel_hi:[0,1,1]
	v_mov_b32_e32 v36, v38
	v_mov_b32_e32 v37, v46
	v_pk_fma_f32 v[26:27], v[42:43], v[36:37], v[26:27] op_sel_hi:[0,1,1]
	v_mov_b32_e32 v36, v28
	v_mov_b32_e32 v37, v32
	v_pk_fma_f32 v[30:31], v[34:35], v[36:37], v[30:31] op_sel_hi:[0,1,1]
	v_mov_b32_e32 v32, v29
	v_mov_b32_e32 v46, v39
	v_pk_fma_f32 v[32:33], v[92:93], v[32:33], v[30:31] op_sel_hi:[0,1,1]
	ds_read_b128 v[28:31], v128 offset:32800
	ds_read_b128 v[36:39], v128 offset:36896
	v_pk_fma_f32 v[26:27], v[74:75], v[46:47], v[26:27] op_sel_hi:[0,1,1]
	s_waitcnt lgkmcnt(1)
	v_mov_b32_e32 v40, v28
	s_waitcnt lgkmcnt(0)
	v_mov_b32_e32 v41, v36
	v_pk_fma_f32 v[32:33], v[66:67], v[40:41], v[32:33] op_sel_hi:[0,1,1]
	v_mov_b32_e32 v36, v29
	v_pk_fma_f32 v[28:29], v[88:89], v[36:37], v[32:33] op_sel_hi:[0,1,1]
	v_mov_b32_e32 v32, v30
	v_mov_b32_e32 v33, v38
	v_pk_fma_f32 v[28:29], v[62:63], v[32:33], v[28:29] op_sel_hi:[0,1,1]
	v_mov_b32_e32 v38, v31
	v_pk_fma_f32 v[32:33], v[90:91], v[38:39], v[28:29] op_sel_hi:[0,1,1]
	ds_read_b128 v[28:31], v128 offset:32816
	ds_read_b128 v[36:39], v128 offset:36912
	s_waitcnt lgkmcnt(1)
	v_mov_b32_e32 v40, v28
	s_waitcnt lgkmcnt(0)
	v_mov_b32_e32 v41, v36
	v_pk_fma_f32 v[32:33], v[54:55], v[40:41], v[32:33] op_sel_hi:[0,1,1]
	v_mov_b32_e32 v36, v29
	v_pk_fma_f32 v[28:29], v[86:87], v[36:37], v[32:33] op_sel_hi:[0,1,1]
	v_mov_b32_e32 v32, v30
	v_mov_b32_e32 v33, v38
	v_pk_fma_f32 v[28:29], v[42:43], v[32:33], v[28:29] op_sel_hi:[0,1,1]
	v_mov_b32_e32 v38, v31
	v_pk_fma_f32 v[96:97], v[74:75], v[38:39], v[28:29] op_sel_hi:[0,1,1]
	v_mov_b32_e32 v28, v20
	v_mov_b32_e32 v29, v24
	v_pk_fma_f32 v[22:23], v[34:35], v[28:29], v[22:23] op_sel_hi:[0,1,1]
	v_mov_b32_e32 v24, v21
	v_pk_fma_f32 v[24:25], v[92:93], v[24:25], v[22:23] op_sel_hi:[0,1,1]
	ds_read_b128 v[20:23], v128 offset:40992
	ds_read_b128 v[28:31], v128 offset:45088
	s_waitcnt lgkmcnt(1)
	v_mov_b32_e32 v32, v20
	s_waitcnt lgkmcnt(0)
	v_mov_b32_e32 v33, v28
	v_pk_fma_f32 v[24:25], v[66:67], v[32:33], v[24:25] op_sel_hi:[0,1,1]
	v_mov_b32_e32 v28, v21
	v_pk_fma_f32 v[20:21], v[88:89], v[28:29], v[24:25] op_sel_hi:[0,1,1]
	v_mov_b32_e32 v24, v22
	v_mov_b32_e32 v25, v30
	v_pk_fma_f32 v[20:21], v[62:63], v[24:25], v[20:21] op_sel_hi:[0,1,1]
	v_mov_b32_e32 v30, v23
	v_pk_fma_f32 v[24:25], v[90:91], v[30:31], v[20:21] op_sel_hi:[0,1,1]
	ds_read_b128 v[20:23], v128 offset:41008
	ds_read_b128 v[28:31], v128 offset:45104
	s_waitcnt lgkmcnt(1)
; __device__ void mod_job(const Params& p, int job, char* smem) {
;     ...
;     for (int u = 0; u < 16; ++u)
; #pragma unroll
;       for (int r = 0; r < 17; ++r) acc[r] += sc[r * 1024 + k + u] * wv[u];
;   }
; #pragma unroll
;   for (int r = 0; r < 17; ++r) red[(kq * 17 + r) * 64 + col] = acc[r];
;   __syncthreads();
;   for (int i = tid; i < 17 * 64; i += NTHR) {
;     const int r = i >> 6, cc = i & 63;
;     float s = p.b_mod[l * 6144 + n0 + cc];
; #pragma unroll
;     for (int q = 0; q < 8; ++q) s += red[(q * 17 + r) * 64 + cc];
	v_mov_b32_e32 v32, v20
	s_waitcnt lgkmcnt(0)
	v_mov_b32_e32 v33, v28
	v_pk_fma_f32 v[24:25], v[54:55], v[32:33], v[24:25] op_sel_hi:[0,1,1]
	v_mov_b32_e32 v28, v21
	v_pk_fma_f32 v[20:21], v[86:87], v[28:29], v[24:25] op_sel_hi:[0,1,1]
	v_mov_b32_e32 v24, v22
	v_mov_b32_e32 v25, v30
	v_pk_fma_f32 v[20:21], v[42:43], v[24:25], v[20:21] op_sel_hi:[0,1,1]
	v_mov_b32_e32 v30, v23
	v_pk_fma_f32 v[98:99], v[74:75], v[30:31], v[20:21] op_sel_hi:[0,1,1]
	v_mov_b32_e32 v20, v12
	v_mov_b32_e32 v21, v16
	v_pk_fma_f32 v[14:15], v[34:35], v[20:21], v[14:15] op_sel_hi:[0,1,1]
	v_mov_b32_e32 v16, v13
	v_pk_fma_f32 v[16:17], v[92:93], v[16:17], v[14:15] op_sel_hi:[0,1,1]
	ds_read_b128 v[12:15], v128 offset:49184
	ds_read_b128 v[20:23], v128 offset:53280
	s_waitcnt lgkmcnt(1)
	v_mov_b32_e32 v24, v12
	s_waitcnt lgkmcnt(0)
	v_mov_b32_e32 v25, v20
	v_pk_fma_f32 v[16:17], v[66:67], v[24:25], v[16:17] op_sel_hi:[0,1,1]
	v_mov_b32_e32 v20, v13
	v_pk_fma_f32 v[12:13], v[88:89], v[20:21], v[16:17] op_sel_hi:[0,1,1]
	v_mov_b32_e32 v16, v14
	v_mov_b32_e32 v17, v22
	v_pk_fma_f32 v[12:13], v[62:63], v[16:17], v[12:13] op_sel_hi:[0,1,1]
	v_mov_b32_e32 v22, v15
	v_pk_fma_f32 v[12:13], v[90:91], v[22:23], v[12:13] op_sel_hi:[0,1,1]
	ds_read_b128 v[14:17], v128 offset:49200
	ds_read_b128 v[20:23], v128 offset:53296
	s_waitcnt lgkmcnt(1)
	v_mov_b32_e32 v24, v14
	s_waitcnt lgkmcnt(0)
	v_mov_b32_e32 v25, v20
	v_pk_fma_f32 v[12:13], v[54:55], v[24:25], v[12:13] op_sel_hi:[0,1,1]
	v_mov_b32_e32 v20, v15
	v_pk_fma_f32 v[12:13], v[86:87], v[20:21], v[12:13] op_sel_hi:[0,1,1]
	v_mov_b32_e32 v14, v16
	v_mov_b32_e32 v15, v22
	v_pk_fma_f32 v[12:13], v[42:43], v[14:15], v[12:13] op_sel_hi:[0,1,1]
	v_mov_b32_e32 v22, v17
	v_pk_fma_f32 v[100:101], v[74:75], v[22:23], v[12:13] op_sel_hi:[0,1,1]
	v_mov_b32_e32 v12, v4
	v_mov_b32_e32 v13, v8
	v_pk_fma_f32 v[6:7], v[34:35], v[12:13], v[6:7] op_sel_hi:[0,1,1]
	v_mov_b32_e32 v8, v5
	v_pk_fma_f32 v[8:9], v[92:93], v[8:9], v[6:7] op_sel_hi:[0,1,1]
	ds_read_b128 v[4:7], v128 offset:57376
	ds_read_b128 v[12:15], v128 offset:61472
	s_waitcnt lgkmcnt(1)
	v_mov_b32_e32 v16, v4
	s_waitcnt lgkmcnt(0)
	v_mov_b32_e32 v17, v12
	v_pk_fma_f32 v[8:9], v[66:67], v[16:17], v[8:9] op_sel_hi:[0,1,1]
	v_mov_b32_e32 v12, v5
	v_pk_fma_f32 v[4:5], v[88:89], v[12:13], v[8:9] op_sel_hi:[0,1,1]
	v_mov_b32_e32 v8, v6
	v_mov_b32_e32 v9, v14
	v_pk_fma_f32 v[4:5], v[62:63], v[8:9], v[4:5] op_sel_hi:[0,1,1]
	v_mov_b32_e32 v14, v7
	v_pk_fma_f32 v[8:9], v[90:91], v[14:15], v[4:5] op_sel_hi:[0,1,1]
	ds_read_b128 v[4:7], v128 offset:57392
	ds_read_b128 v[12:15], v128 offset:61488
	s_waitcnt lgkmcnt(1)
	v_mov_b32_e32 v16, v4
	s_waitcnt lgkmcnt(0)
	v_mov_b32_e32 v17, v12
	v_pk_fma_f32 v[8:9], v[54:55], v[16:17], v[8:9] op_sel_hi:[0,1,1]
	v_mov_b32_e32 v12, v5
	v_pk_fma_f32 v[4:5], v[86:87], v[12:13], v[8:9] op_sel_hi:[0,1,1]
	v_mov_b32_e32 v8, v6
	v_mov_b32_e32 v9, v14
	v_pk_fma_f32 v[4:5], v[42:43], v[8:9], v[4:5] op_sel_hi:[0,1,1]
	v_mov_b32_e32 v14, v7
	v_pk_fma_f32 v[102:103], v[74:75], v[14:15], v[4:5] op_sel_hi:[0,1,1]
	v_add_u32_e32 v4, 0x1003c, v128
	ds_read_b32 v4, v4
	v_add_u32_e32 v128, 64, v128
	s_waitcnt lgkmcnt(0)
	v_fmac_f32_e32 v129, v74, v4
	s_andn2_b64 exec, exec, s[6:7]
	s_cbranch_execnz .LBB0_48
	s_or_b64 exec, exec, s[6:7]
	v_lshl_add_u32 v4, v79, 2, s38
	s_movk_i32 s2, 0x1100
	v_mad_u64_u32 v[6:7], s[2:3], v83, s2, v[4:5]
	s_movk_i32 s2, 0x440
	s_nop 0
	v_cmp_gt_i32_e32 vcc, s2, v82
	ds_write2st64_b32 v6, v2, v3 offset1:1
	ds_write2st64_b32 v6, v10, v11 offset0:2 offset1:3
	ds_write2st64_b32 v6, v18, v19 offset0:4 offset1:5
	ds_write2st64_b32 v6, v26, v27 offset0:6 offset1:7
	ds_write2st64_b32 v6, v96, v97 offset0:8 offset1:9
	ds_write2st64_b32 v6, v98, v99 offset0:10 offset1:11
	ds_write2st64_b32 v6, v100, v101 offset0:12 offset1:13
	ds_write2st64_b32 v6, v102, v103 offset0:14 offset1:15
	ds_write_b32 v6, v129 offset:4096
	s_waitcnt lgkmcnt(0)
	s_barrier
	s_and_saveexec_b64 s[2:3], vcc
	s_cbranch_execz .LBB0_52
	s_load_dwordx16 s[60:75], s[0:1], 0x0
	s_mul_i32 s5, s8, 0x1800
	s_add_i32 s5, s5, s4
	s_and_b32 s4, s4, 0x3c0
	v_or_b32_e32 v2, s5, v79
	v_or_b32_e32 v5, s4, v79
	s_ashr_i32 s6, s9, 4
	v_ashrrev_i32_e32 v3, 31, v2
	v_lshlrev_b32_e32 v74, 2, v5
	s_mul_i32 s8, s8, 17
	s_ashr_i32 s7, s6, 31
	s_waitcnt lgkmcnt(0)
	v_lshl_add_u64 v[2:3], v[2:3], 2, s[70:71]
	v_lshl_add_u64 v[6:7], s[44:45], 0, v[74:75]
	s_mov_b64 s[4:5], 0
